# shorter grid-barrier tail: all workgroups poll the cross-XCC arrival counter
# speedup vs baseline: 1.0020x; 1.0020x over previous
.LBB0_270:
	s_waitcnt lgkmcnt(0)
	v_readfirstlane_b32 s98, v2
	v_readfirstlane_b32 s99, v0
	s_lshl_b32 s3, s33, 8
	s_add_u32 s100, s34, s3
	s_addc_u32 s101, s35, 0
	v_mov_b32_e32 v1, 0x1000
	v_mov_b32_e32 v3, 1
	v_mov_b32_e32 v5, 1
	v_mov_b32_e32 v4, 0x3400
	s_nop 4
	global_atomic_add v3, v1, v3, s[100:101] offset:1024 sc0
	s_mul_i32 s98, s98, 1
	s_mul_i32 s99, s99, 1
	s_waitcnt vmcnt(0)
	v_readfirstlane_b32 s3, v3
	s_nop 3
	s_add_i32 s3, s3, 1
	s_cmp_lg_u32 s3, s98
	s_cbranch_scc1 .Lmy_bw_0_270
	buffer_wbl2 sc1
	s_waitcnt vmcnt(0)
	global_atomic_add v4, v5, s[34:35]
.Lmy_bw_0_270:
	s_mov_b32 s3, 0
.Lmy_bp_0_270:
	global_load_dword v3, v4, s[34:35] sc1
	s_add_i32 s3, s3, 1
	s_waitcnt vmcnt(0)
	v_readfirstlane_b32 s98, v3
	s_nop 3
	s_cmp_ge_u32 s98, s99
	s_cbranch_scc1 .Lmy_bd_0_270
	s_cmp_lt_u32 s3, 0x400000
	s_cbranch_scc1 .Lmy_bp_0_270
.Lmy_bd_0_270:
	buffer_inv sc1
	s_waitcnt vmcnt(0)

.LBB0_359:
	s_waitcnt lgkmcnt(0)
	v_readfirstlane_b32 s98, v2
	v_readfirstlane_b32 s99, v0
	s_lshl_b32 s3, s33, 8
	s_add_u32 s100, s34, s3
	s_addc_u32 s101, s35, 0
	v_mov_b32_e32 v1, 0x1000
	v_mov_b32_e32 v3, 1
	v_mov_b32_e32 v5, 1
	v_mov_b32_e32 v4, 0x3400
	s_nop 4
	global_atomic_add v3, v1, v3, s[100:101] offset:1024 sc0
	s_mul_i32 s98, s98, 2
	s_mul_i32 s99, s99, 2
	s_waitcnt vmcnt(0)
	v_readfirstlane_b32 s3, v3
	s_nop 3
	s_add_i32 s3, s3, 1
	s_cmp_lg_u32 s3, s98
	s_cbranch_scc1 .Lmy_bw_1_359
	buffer_wbl2 sc1
	s_waitcnt vmcnt(0)
	global_atomic_add v4, v5, s[34:35]

.LBB0_492:
	s_waitcnt lgkmcnt(0)
	v_readfirstlane_b32 s98, v2
	v_readfirstlane_b32 s99, v0
	s_lshl_b32 s3, s33, 8
	s_add_u32 s100, s34, s3
	s_addc_u32 s101, s35, 0
	v_mov_b32_e32 v1, 0x1000
	v_mov_b32_e32 v3, 1
	v_mov_b32_e32 v5, 1
	v_mov_b32_e32 v4, 0x3400
	s_nop 4
	global_atomic_add v3, v1, v3, s[100:101] offset:1024 sc0
	s_mul_i32 s98, s98, 3
	s_mul_i32 s99, s99, 3
	s_waitcnt vmcnt(0)
	v_readfirstlane_b32 s3, v3
	s_nop 3
	s_add_i32 s3, s3, 1
	s_cmp_lg_u32 s3, s98
	s_cbranch_scc1 .Lmy_bw_2_492
	buffer_wbl2 sc1
	s_waitcnt vmcnt(0)
	global_atomic_add v4, v5, s[34:35]

.LBB0_585:
	s_waitcnt lgkmcnt(0)
	v_readfirstlane_b32 s98, v2
	v_readfirstlane_b32 s99, v0
	s_lshl_b32 s3, s33, 8
	s_add_u32 s100, s34, s3
	s_addc_u32 s101, s35, 0
	v_mov_b32_e32 v1, 0x1000
	v_mov_b32_e32 v3, 1
	v_mov_b32_e32 v5, 1
	v_mov_b32_e32 v4, 0x3400
	s_nop 4
	global_atomic_add v3, v1, v3, s[100:101] offset:1024 sc0
	s_mul_i32 s98, s98, 4
	s_mul_i32 s99, s99, 4
	s_waitcnt vmcnt(0)
	v_readfirstlane_b32 s3, v3
	s_nop 3
	s_add_i32 s3, s3, 1
	s_cmp_lg_u32 s3, s98
	s_cbranch_scc1 .Lmy_bw_3_585
	buffer_wbl2 sc1
	s_waitcnt vmcnt(0)
	global_atomic_add v4, v5, s[34:35]

.LBB0_671:
	s_waitcnt lgkmcnt(0)
	v_readfirstlane_b32 s98, v2
	v_readfirstlane_b32 s99, v0
	s_lshl_b32 s3, s33, 8
	s_add_u32 s100, s34, s3
	s_addc_u32 s101, s35, 0
	v_mov_b32_e32 v1, 0x1000
	v_mov_b32_e32 v3, 1
	v_mov_b32_e32 v5, 1
	v_mov_b32_e32 v4, 0x3400
	s_nop 4
	global_atomic_add v3, v1, v3, s[100:101] offset:1024 sc0
	s_mul_i32 s98, s98, 5
	s_mul_i32 s99, s99, 5
	s_waitcnt vmcnt(0)
	v_readfirstlane_b32 s3, v3
	s_nop 3
	s_add_i32 s3, s3, 1
	s_cmp_lg_u32 s3, s98
	s_cbranch_scc1 .Lmy_bw_4_671
	buffer_wbl2 sc1
	s_waitcnt vmcnt(0)
	global_atomic_add v4, v5, s[34:35]

	.amdhsa_kernel _Z9block_fwd4Args
		.amdhsa_group_segment_fixed_size 0
		.amdhsa_private_segment_fixed_size 0
		.amdhsa_kernarg_size 408
		.amdhsa_user_sgpr_count 2
		.amdhsa_user_sgpr_dispatch_ptr 0
		.amdhsa_user_sgpr_queue_ptr 0
		.amdhsa_user_sgpr_kernarg_segment_ptr 1
		.amdhsa_user_sgpr_dispatch_id 0
		.amdhsa_user_sgpr_kernarg_preload_length 0
		.amdhsa_user_sgpr_kernarg_preload_offset 0
		.amdhsa_user_sgpr_private_segment_size 0
		.amdhsa_uses_dynamic_stack 0
		.amdhsa_enable_private_segment 0
		.amdhsa_system_sgpr_workgroup_id_x 1
		.amdhsa_system_sgpr_workgroup_id_y 0
		.amdhsa_system_sgpr_workgroup_id_z 0
		.amdhsa_system_sgpr_workgroup_info 0
		.amdhsa_system_vgpr_workitem_id 2
		.amdhsa_next_free_vgpr 237
		.amdhsa_next_free_sgpr 102
		.amdhsa_accum_offset 240
		.amdhsa_reserve_vcc 1
		.amdhsa_float_round_mode_32 0
		.amdhsa_float_round_mode_16_64 0
		.amdhsa_float_denorm_mode_32 3
		.amdhsa_float_denorm_mode_16_64 3
		.amdhsa_dx10_clamp 1
		.amdhsa_ieee_mode 1
		.amdhsa_fp16_overflow 0
		.amdhsa_tg_split 0
		.amdhsa_exception_fp_ieee_invalid_op 0
		.amdhsa_exception_fp_denorm_src 0
		.amdhsa_exception_fp_ieee_div_zero 0
		.amdhsa_exception_fp_ieee_overflow 0
		.amdhsa_exception_fp_ieee_underflow 0
		.amdhsa_exception_fp_ieee_inexact 0
		.amdhsa_exception_int_div_zero 0
	.end_amdhsa_kernel

amdhsa.kernels:
  - .agpr_count:     0
    .args:
      - .offset:         0
        .size:           152
        .value_kind:     by_value
      - .offset:         152
        .size:           4
        .value_kind:     hidden_block_count_x
      - .offset:         156
        .size:           4
        .value_kind:     hidden_block_count_y
      - .offset:         160
        .size:           4
        .value_kind:     hidden_block_count_z
      - .offset:         164
        .size:           2
        .value_kind:     hidden_group_size_x
      - .offset:         166
        .size:           2
        .value_kind:     hidden_group_size_y
      - .offset:         168
        .size:           2
        .value_kind:     hidden_group_size_z
      - .offset:         170
        .size:           2
        .value_kind:     hidden_remainder_x
      - .offset:         172
        .size:           2
        .value_kind:     hidden_remainder_y
      - .offset:         174
        .size:           2
        .value_kind:     hidden_remainder_z
      - .offset:         192
        .size:           8
        .value_kind:     hidden_global_offset_x
      - .offset:         200
        .size:           8
        .value_kind:     hidden_global_offset_y
      - .offset:         208
        .size:           8
        .value_kind:     hidden_global_offset_z
      - .offset:         216
        .size:           2
        .value_kind:     hidden_grid_dims
      - .offset:         240
        .size:           8
        .value_kind:     hidden_multigrid_sync_arg
      - .offset:         272
        .size:           4
        .value_kind:     hidden_dynamic_lds_size
    .group_segment_fixed_size: 0
    .kernarg_segment_align: 8
    .kernarg_segment_size: 408
    .language:       OpenCL C
    .language_version:
      - 2
      - 0
    .max_flat_workgroup_size: 512
    .name:           _Z9block_fwd4Args
    .private_segment_fixed_size: 0
    .sgpr_count:     108
    .sgpr_spill_count: 5
    .symbol:         _Z9block_fwd4Args.kd
    .uniform_work_group_size: 1
    .uses_dynamic_stack: false
    .vgpr_count:     237
    .vgpr_spill_count: 0
    .wavefront_size: 64
